# attention main loop: K/V tiles staged by LDS-DMA (swizzled per-lane source addresses), one workgroup barrier per half-iteration, no VGPR staging / LDS writes
# speedup vs baseline: 1.0132x; 1.0132x over previous
.LBB0_432:
	s_ashr_i32 s69, s59, 6
	s_lshl_b32 s3, s59, 8
	s_lshl_b32 s2, s69, 11
	s_and_b32 s3, s3, 0x700
	s_bfe_u32 s6, s59, 0x10005
	s_or_b32 s26, s2, s3
	s_lshl_b32 s3, s59, 4
	s_ashr_i32 s27, s26, 31
	s_lshl_b32 s2, s6, 9
	s_and_b32 s3, s3, 0x180
	s_lshl_b32 s68, s6, 8
	s_or_b32 s63, s2, s3
	s_lshl_b64 s[2:3], s[26:27], 11
	s_add_u32 s2, s22, s2
	s_addc_u32 s3, s23, s3
	s_lshl_b32 s7, s63, 1
	s_add_u32 s8, s2, s7
	s_mul_i32 s2, s69, 0x1200
	s_addc_u32 s9, s3, 0
	s_mul_hi_i32 s3, s69, 0x1200
	s_or_b32 s2, s2, s6
	v_mov_b32_e32 v68, v208
	s_lshl_b64 s[6:7], s[2:3], 8
	s_add_u32 s2, s24, s6
	v_ashrrev_i32_e32 v16, 4, v68
	v_lshlrev_b32_e32 v22, 3, v68
	v_add_u32_e32 v18, 32, v16
	s_addc_u32 s3, s25, s7
	v_and_b32_e32 v0, 0x78, v22
	v_ashrrev_i32_e32 v17, 31, v16
	v_ashrrev_i32_e32 v19, 31, v18
	s_add_u32 s6, s1, s6
	v_lshlrev_b32_e32 v23, 1, v0
	v_lshlrev_b64 v[48:49], 9, v[16:17]
	v_lshlrev_b64 v[8:9], 9, v[18:19]
	s_addc_u32 s7, s54, s7
	v_or_b32_e32 v50, v48, v23
	v_mov_b32_e32 v51, v49
	v_or_b32_e32 v8, v8, v23
	v_ashrrev_i32_e32 v155, 6, v68
	s_add_u32 s82, s2, 0x10000
	s_addc_u32 s83, s3, 0
	s_add_u32 s84, s6, 0x10000
	s_addc_u32 s85, s7, 0
	v_lshl_add_u64 v[0:1], s[6:7], 0, v[50:51]
	v_lshl_add_u64 v[4:5], s[6:7], 0, v[8:9]
	v_lshl_add_u64 v[10:11], s[2:3], 0, v[50:51]
	v_lshl_add_u64 v[12:13], s[2:3], 0, v[8:9]
	v_and_b32_e32 v154, 31, v68
	v_lshlrev_b32_e32 v130, 5, v155
	v_lshl_add_u64 v[218:219], v[0:1], 0, s[16:17]
	v_lshl_add_u64 v[222:223], v[4:5], 0, s[16:17]
	v_lshl_add_u64 v[226:227], v[10:11], 0, s[16:17]
	v_lshl_add_u64 v[230:231], v[12:13], 0, s[16:17]
	global_load_dwordx4 v[0:3], v[0:1], off
	s_nop 0
	global_load_dwordx4 v[4:7], v[4:5], off
	s_nop 0
	global_load_dwordx4 v[8:11], v[10:11], off
	s_nop 0
	global_load_dwordx4 v[12:15], v[12:13], off
	v_or_b32_e32 v20, v130, v154
	v_ashrrev_i32_e32 v21, 31, v20
	v_bfe_u32 v153, v68, 5, 1
	v_lshlrev_b64 v[20:21], 11, v[20:21]
	v_lshl_add_u64 v[20:21], s[8:9], 0, v[20:21]
	v_lshlrev_b32_e32 v128, 4, v153
	v_lshl_add_u64 v[20:21], v[20:21], 0, v[128:129]
	global_load_dwordx4 v[124:127], v[20:21], off
	global_load_dwordx4 v[120:123], v[20:21], off offset:32
	global_load_dwordx4 v[112:115], v[20:21], off offset:64
	global_load_dwordx4 v[116:119], v[20:21], off offset:96
	global_load_dwordx4 v[108:111], v[20:21], off offset:128
	global_load_dwordx4 v[104:107], v[20:21], off offset:160
	global_load_dwordx4 v[100:103], v[20:21], off offset:192
	global_load_dwordx4 v[96:99], v[20:21], off offset:224
	global_load_dwordx4 v[218:221], v[218:219], off
	global_load_dwordx4 v[222:225], v[222:223], off
	global_load_dwordx4 v[226:229], v[226:227], off
	global_load_dwordx4 v[230:233], v[230:231], off
	v_and_b32_e32 v19, 0xfffff0, v16
	v_lshlrev_b32_e32 v24, 1, v16
	v_lshrrev_b32_e32 v25, 1, v16
	v_and_b32_e32 v26, 3, v16
	v_and_or_b32 v19, v16, 8, v19
	v_and_or_b32 v24, v16, 4, v26
	v_and_b32_e32 v25, 0xfffff0, v18
	v_and_or_b32 v25, v18, 8, v25
	v_lshlrev_b32_e32 v26, 1, v18
	v_and_b32_e32 v17, 0x70, v68
	v_bfe_u32 v22, v22, 5, 2
	v_lshlrev_b32_e32 v16, 8, v16
	v_lshlrev_b32_e32 v18, 8, v18
	v_lshrrev_b32_e32 v19, 1, v19
	v_lshlrev_b32_e32 v156, 4, v68
	v_bitop3_b32 v162, v23, v16, v17 bitop3:0xde
	v_bitop3_b32 v163, v23, v18, v17 bitop3:0xde
	v_or_b32_e32 v16, v19, v22
	v_lshrrev_b32_e32 v17, 1, v25
	v_lshlrev_b32_e32 v24, 6, v24
	v_and_b32_e32 v27, 48, v23
	v_lshlrev_b32_e32 v16, 9, v16
	v_or_b32_e32 v17, v17, v22
	v_lshlrev_b32_e32 v60, 8, v154
	v_and_b32_e32 v61, 0x70, v156
	v_or3_b32 v164, v16, v24, v27
	v_lshlrev_b32_e32 v16, 9, v17
	v_bitop3_b32 v166, v128, v60, v61 bitop3:0xde
	v_or3_b32 v165, v16, v24, v27
	s_waitcnt vmcnt(0)
	v_and_b32_e32 v62, 0x3fffffc0, v68
	v_and_b32_e32 v157, 63, v68
	v_lshlrev_b32_e32 v63, 1, v68
	v_lshl_add_u32 v131, v62, 2, v150
	v_lshlrev_b32_e32 v62, 3, v157
	v_lshl_or_b32 v158, v154, 2, v131
	s_waitcnt vmcnt(11)
	ds_write_b128 v164, v[0:3]
	s_waitcnt vmcnt(10)
	ds_write_b128 v165, v[4:7]
	s_waitcnt vmcnt(9)
	ds_write_b128 v162, v[8:11] offset:32768
	s_waitcnt vmcnt(8)
	ds_write_b128 v163, v[12:15] offset:32768
	s_waitcnt lgkmcnt(0)
	s_barrier
	ds_read_b128 v[0:3], v166 offset:32768
	ds_read_b128 v[4:7], v166 offset:40960
	s_waitcnt vmcnt(7) lgkmcnt(1)
	v_mfma_f32_32x32x16_bf16 v[32:47], v[0:3], v[124:127], 0
	v_or_b32_e32 v0, 32, v128
	v_bitop3_b32 v167, v0, v60, v61 bitop3:0xde
	v_mov_b32_e32 v159, 0
	s_waitcnt lgkmcnt(0)
	v_mfma_f32_32x32x16_bf16 v[16:31], v[4:7], v[124:127], 0
	ds_read_b128 v[0:3], v167 offset:32768
	ds_read_b128 v[4:7], v167 offset:40960
	s_waitcnt vmcnt(6) lgkmcnt(1)
	v_mfma_f32_32x32x16_bf16 v[32:47], v[0:3], v[120:123], v[32:47]
	v_or_b32_e32 v0, 64, v128
	v_bitop3_b32 v168, v0, v60, v61 bitop3:0xde
	s_waitcnt lgkmcnt(0)
	v_mfma_f32_32x32x16_bf16 v[16:31], v[4:7], v[120:123], v[16:31]
	ds_read_b128 v[0:3], v168 offset:32768
	ds_read_b128 v[4:7], v168 offset:40960
	s_waitcnt vmcnt(5) lgkmcnt(1)
	v_mfma_f32_32x32x16_bf16 v[32:47], v[0:3], v[112:115], v[32:47]
	v_or_b32_e32 v0, 0x60, v128
	v_bitop3_b32 v169, v0, v60, v61 bitop3:0xde
	s_waitcnt lgkmcnt(0)
	v_mfma_f32_32x32x16_bf16 v[16:31], v[4:7], v[112:115], v[16:31]
	ds_read_b128 v[0:3], v169 offset:32768
	ds_read_b128 v[4:7], v169 offset:40960
	s_waitcnt vmcnt(4) lgkmcnt(1)
	v_mfma_f32_32x32x16_bf16 v[32:47], v[0:3], v[116:119], v[32:47]
	v_or_b32_e32 v0, 0x80, v128
	v_bitop3_b32 v170, v0, v60, v61 bitop3:0xde
	s_waitcnt lgkmcnt(0)
	v_mfma_f32_32x32x16_bf16 v[16:31], v[4:7], v[116:119], v[16:31]
	ds_read_b128 v[0:3], v170 offset:32768
	ds_read_b128 v[4:7], v170 offset:40960
	s_waitcnt vmcnt(3) lgkmcnt(1)
	v_mfma_f32_32x32x16_bf16 v[32:47], v[0:3], v[108:111], v[32:47]
	v_or_b32_e32 v0, 0xa0, v128
	v_bitop3_b32 v171, v0, v60, v61 bitop3:0xde
	s_waitcnt lgkmcnt(0)
	v_mfma_f32_32x32x16_bf16 v[16:31], v[4:7], v[108:111], v[16:31]
	ds_read_b128 v[0:3], v171 offset:32768
	ds_read_b128 v[4:7], v171 offset:40960
	s_waitcnt vmcnt(2) lgkmcnt(1)
	v_mfma_f32_32x32x16_bf16 v[32:47], v[0:3], v[104:107], v[32:47]
	v_or_b32_e32 v0, 0xc0, v128
	v_bitop3_b32 v172, v0, v60, v61 bitop3:0xde
	ds_read_b128 v[52:55], v172 offset:32768
	ds_read_b128 v[56:59], v172 offset:40960
	s_waitcnt lgkmcnt(2)
	v_mfma_f32_32x32x16_bf16 v[16:31], v[4:7], v[104:107], v[16:31]
	v_mov_b64_e32 v[0:1], s[36:37]
	v_mov_b64_e32 v[14:15], s[50:51]
	v_mov_b64_e32 v[2:3], s[38:39]
	v_mov_b64_e32 v[4:5], s[40:41]
	v_mov_b64_e32 v[6:7], s[42:43]
	v_mov_b64_e32 v[8:9], s[44:45]
	v_mov_b64_e32 v[10:11], s[46:47]
	s_waitcnt vmcnt(1) lgkmcnt(1)
	v_mfma_f32_32x32x16_bf16 v[32:47], v[52:55], v[100:103], v[32:47]
	v_or_b32_e32 v52, 0xe0, v128
	v_bitop3_b32 v173, v52, v60, v61 bitop3:0xde
	ds_read_b128 v[52:55], v173 offset:32768
	v_lshl_add_u64 v[60:61], v[50:51], 0, s[16:17]
	v_lshl_add_u64 v[50:51], v[50:51], 0, s[18:19]
	v_lshl_add_u64 v[64:65], s[2:3], 0, v[50:51]
	v_mov_b64_e32 v[12:13], s[48:49]
	s_waitcnt lgkmcnt(1)
	v_mfma_f32_32x32x16_bf16 v[16:31], v[56:59], v[100:103], v[16:31]
	v_and_b32_e32 v56, 0xc0, v156
	v_and_b32_e32 v57, 32, v63
	v_and_or_b32 v56, v62, 24, v56
	v_and_b32_e32 v58, 0x100, v62
	v_or3_b32 v161, v56, v57, v58
	ds_read_b128 v[56:59], v173 offset:40960
	v_or_b32_e32 v160, 0x4000, v161
	s_waitcnt vmcnt(0) lgkmcnt(1)
	v_mfma_f32_32x32x16_bf16 v[32:47], v[52:55], v[96:99], v[32:47]
	v_lshl_add_u64 v[54:55], s[2:3], 0, v[60:61]
	v_lshl_add_u64 v[52:53], s[6:7], 0, v[60:61]
	v_lshl_add_u64 v[60:61], s[6:7], 0, v[50:51]
	s_nop 0
	v_cmp_gt_u32_e64 s[6:7], 32, v157
	s_waitcnt lgkmcnt(0)
	v_mfma_f32_32x32x16_bf16 v[16:31], v[56:59], v[96:99], v[16:31]
	s_nop 0
	v_max_f32_e32 v58, v33, v33
	v_max_f32_e32 v59, v32, v32
	v_max_f32_e32 v58, v59, v58
	v_max3_f32 v58, v58, v34, v35
	v_max3_f32 v58, v58, v36, v37
	v_max3_f32 v58, v58, v38, v39
	v_max3_f32 v58, v58, v40, v41
	v_max3_f32 v58, v58, v42, v43
	v_max3_f32 v58, v58, v44, v45
	v_max3_f32 v58, v58, v46, v47
	v_max3_f32 v58, v58, v16, v17
	v_max3_f32 v58, v58, v18, v19
	v_max3_f32 v58, v58, v20, v21
	v_max3_f32 v58, v58, v22, v23
	v_max3_f32 v58, v58, v24, v25
	v_max3_f32 v58, v58, v26, v27
	v_max3_f32 v58, v58, v28, v29
	v_max3_f32 v58, v58, v30, v31
	v_mov_b32_e32 v59, v58
	s_nop 1
	v_permlane32_swap_b32_e32 v58, v59
	v_max_f32_e32 v59, v59, v59
	v_max_f32_e32 v58, v58, v58
	v_max_f32_e32 v58, v58, v59
	v_add_f32_e32 v59, 0x7149f2ca, v58
	v_max_f32_e32 v58, 0xf149f2ca, v58
	v_cmp_ge_f32_e32 vcc, s15, v59
	v_sub_f32_e32 v59, 0xf149f2ca, v58
	v_mul_f32_e32 v59, 0x3e0293ee, v59
	v_exp_f32_e32 v59, v59
	s_cmp_eq_u64 vcc, exec
	s_cselect_b64 vcc, -1, 0
	v_cndmask_b32_e32 v175, v58, v151, vcc
	v_mul_f32_e32 v58, 0xbe0293ee, v175
	v_cndmask_b32_e64 v174, v59, 1.0, vcc
	v_mov_b32_e32 v59, v58
	v_fmac_f32_e32 v59, 0x3e0293ee, v47
	v_fmamk_f32 v32, v32, 0x3e0293ee, v58
	v_fmamk_f32 v33, v33, 0x3e0293ee, v58
	v_fmamk_f32 v34, v34, 0x3e0293ee, v58
	v_fmamk_f32 v35, v35, 0x3e0293ee, v58
	v_fmamk_f32 v36, v36, 0x3e0293ee, v58
	v_fmamk_f32 v37, v37, 0x3e0293ee, v58
	v_fmamk_f32 v38, v38, 0x3e0293ee, v58
	v_fmamk_f32 v39, v39, 0x3e0293ee, v58
	v_fmamk_f32 v40, v40, 0x3e0293ee, v58
	v_fmamk_f32 v41, v41, 0x3e0293ee, v58
	v_fmamk_f32 v42, v42, 0x3e0293ee, v58
	v_fmamk_f32 v43, v43, 0x3e0293ee, v58
	v_fmamk_f32 v44, v44, 0x3e0293ee, v58
	v_fmamk_f32 v45, v45, 0x3e0293ee, v58
	v_fmamk_f32 v46, v46, 0x3e0293ee, v58
	v_pk_fma_f32 v[140:141], v[18:19], s[14:15], v[58:59] op_sel_hi:[1,0,0]
	v_and_b32_e32 v18, 15, v68
	v_pk_fma_f32 v[142:143], v[16:17], s[14:15], v[58:59] op_sel_hi:[1,0,0]
	v_exp_f32_e32 v190, v32
	v_exp_f32_e32 v191, v33
	v_exp_f32_e32 v192, v34
	v_exp_f32_e32 v193, v35
	v_exp_f32_e32 v194, v36
	v_exp_f32_e32 v196, v37
	v_exp_f32_e32 v195, v38
	v_exp_f32_e32 v197, v39
	v_exp_f32_e32 v182, v40
	v_exp_f32_e32 v183, v41
	v_exp_f32_e32 v184, v42
	v_exp_f32_e32 v186, v43
	v_exp_f32_e32 v185, v44
	v_exp_f32_e32 v187, v45
	v_exp_f32_e32 v188, v46
	v_exp_f32_e32 v189, v59
	v_mad_i64_i32 v[16:17], s[2:3], s69, v152, v[48:49]
	v_lshlrev_b32_e32 v18, 4, v18
	s_waitcnt vmcnt(0)
	v_or3_b32 v16, v16, s68, v18
	v_pk_fma_f32 v[144:145], v[30:31], s[14:15], v[58:59] op_sel_hi:[1,0,0]
	v_pk_fma_f32 v[146:147], v[28:29], s[14:15], v[58:59] op_sel_hi:[1,0,0]
	v_pk_fma_f32 v[148:149], v[26:27], s[14:15], v[58:59] op_sel_hi:[1,0,0]
	v_pk_fma_f32 v[134:135], v[24:25], s[14:15], v[58:59] op_sel_hi:[1,0,0]
	v_pk_fma_f32 v[136:137], v[22:23], s[14:15], v[58:59] op_sel_hi:[1,0,0]
	v_pk_fma_f32 v[138:139], v[20:21], s[14:15], v[58:59] op_sel_hi:[1,0,0]
	s_waitcnt vmcnt(3)
	ds_write_b128 v164, v[218:221] offset:16384
	s_waitcnt vmcnt(2)
	ds_write_b128 v165, v[222:225] offset:16384
	s_waitcnt vmcnt(1)
	ds_write_b128 v162, v[226:229] offset:49152
	s_waitcnt vmcnt(0)
	ds_write_b128 v163, v[230:233] offset:49152
	v_lshl_add_u64 v[132:133], s[12:13], 0, v[16:17]
	v_mov_b64_e32 v[62:63], v[14:15]
	v_mov_b64_e32 v[46:47], v[14:15]
	v_mov_b64_e32 v[30:31], v[14:15]
	s_mov_b32 s68, -1
	v_mov_b64_e32 v[60:61], v[12:13]
	v_mov_b64_e32 v[58:59], v[10:11]
	v_mov_b64_e32 v[56:57], v[8:9]
	v_mov_b64_e32 v[54:55], v[6:7]
	v_mov_b64_e32 v[52:53], v[4:5]
	v_mov_b64_e32 v[50:51], v[2:3]
	v_mov_b64_e32 v[48:49], v[0:1]
	v_mov_b64_e32 v[44:45], v[12:13]
	v_mov_b64_e32 v[42:43], v[10:11]
	v_mov_b64_e32 v[40:41], v[8:9]
	v_mov_b64_e32 v[38:39], v[6:7]
	v_mov_b64_e32 v[36:37], v[4:5]
	v_mov_b64_e32 v[34:35], v[2:3]
	v_mov_b64_e32 v[32:33], v[0:1]
	v_mov_b64_e32 v[28:29], v[12:13]
	v_mov_b64_e32 v[26:27], v[10:11]
	v_mov_b64_e32 v[24:25], v[8:9]
	v_mov_b64_e32 v[22:23], v[6:7]
	v_mov_b64_e32 v[20:21], v[4:5]
	v_mov_b64_e32 v[18:19], v[2:3]
	v_mov_b64_e32 v[16:17], v[0:1]
	s_waitcnt lgkmcnt(0)
	s_barrier
	v_lshrrev_b32_e32 v250, 4, v157
	v_and_b32_e32 v251, 15, v157
	v_lshl_add_u32 v252, v155, 3, v250
	v_xor_b32_e32 v253, v251, v250
	v_lshlrev_b32_e32 v253, 4, v253
	v_lshl_add_u32 v247, v252, 9, v253
	v_or_b32_e32 v250, 4, v250
	v_xor_b32_e32 v253, v251, v250
	v_lshlrev_b32_e32 v253, 4, v253
	v_add_u32_e32 v252, 4, v252
	v_lshl_add_u32 v248, v252, 9, v253
	v_bfe_u32 v250, v157, 2, 3
	v_lshl_add_u32 v250, v155, 3, v250
	v_lshrrev_b32_e32 v251, 5, v157
	v_and_b32_e32 v252, 3, v157
	v_lshl_add_u32 v251, v251, 2, v252
	v_lshlrev_b32_e32 v251, 4, v251
	v_lshl_add_u32 v249, v250, 9, v251
	v_readfirstlane_b32 s86, v155
	s_nop 3
	s_lshl_b32 s86, s86, 11
.LBB0_433:
	s_add_u32 m0, s86, 0x8000
	s_nop 0
	global_load_lds_dwordx4 v247, s[82:83]
	s_add_u32 m0, s86, 0x8400
	s_nop 0
	global_load_lds_dwordx4 v248, s[82:83]
	s_add_u32 s82, s82, 0x8000
	s_addc_u32 s83, s83, 0
	ds_read_b128 v[64:67], v166 offset:49152
	ds_read_b128 v[68:71], v166 offset:57344
	ds_read_b128 v[176:179], v167 offset:49152
	ds_read_b128 v[198:201], v167 offset:57344
	ds_read_b128 v[202:205], v168 offset:49152
	ds_read_b128 v[210:213], v168 offset:57344
	v_exp_f32_e32 v142, v142
	v_exp_f32_e32 v143, v143
	s_waitcnt lgkmcnt(5)
	v_mfma_f32_32x32x16_bf16 v[80:95], v[64:67], v[124:127], 0
	v_exp_f32_e32 v180, v140
	v_exp_f32_e32 v181, v141
	v_exp_f32_e32 v206, v138
	v_exp_f32_e32 v207, v135
	v_exp_f32_e32 v148, v148
	v_exp_f32_e32 v149, v149
	v_exp_f32_e32 v209, v146
	s_waitcnt lgkmcnt(4)
	v_mfma_f32_32x32x16_bf16 v[64:79], v[68:71], v[124:127], 0
	v_cvt_pk_bf16_f32 v135, v192, v193
	v_cvt_pk_bf16_f32 v138, v182, v183
	v_cvt_pk_bf16_f32 v140, v185, v187
	v_cvt_pk_bf16_f32 v141, v188, v189
	s_nop 0
	s_waitcnt lgkmcnt(3)
	v_mfma_f32_32x32x16_bf16 v[80:95], v[176:179], v[120:123], v[80:95]
	ds_read_b128 v[176:179], v169 offset:49152
	ds_read_b128 v[214:217], v169 offset:57344
	ds_read_b128 v[218:221], v170 offset:49152
	ds_read_b128 v[222:225], v170 offset:57344
	ds_read_b128 v[226:229], v171 offset:49152
	ds_read_b128 v[230:233], v171 offset:57344
	ds_read_b128 v[234:237], v172 offset:49152
	ds_read_b128 v[238:241], v172 offset:57344
	s_waitcnt lgkmcnt(10)
	v_mfma_f32_32x32x16_bf16 v[64:79], v[198:201], v[120:123], v[64:79]
	ds_read_b128 v[198:201], v173 offset:49152
	ds_read_b128 v[242:245], v173 offset:57344
	s_waitcnt lgkmcnt(11)
	v_mfma_f32_32x32x16_bf16 v[80:95], v[202:205], v[112:115], v[80:95]
	v_exp_f32_e32 v205, v134
	v_add_f32_e32 v134, v191, v190
	v_add_f32_e32 v134, v192, v134
	v_add_f32_e32 v134, v193, v134
	v_add_f32_e32 v134, v194, v134
	v_add_f32_e32 v134, v196, v134
	s_waitcnt lgkmcnt(10)
	v_mfma_f32_32x32x16_bf16 v[64:79], v[210:213], v[112:115], v[64:79]
	v_add_f32_e32 v134, v195, v134
	v_add_f32_e32 v134, v197, v134
	v_add_f32_e32 v134, v182, v134
	v_add_f32_e32 v134, v183, v134
	v_add_f32_e32 v134, v184, v134
	v_add_f32_e32 v134, v186, v134
	v_add_f32_e32 v134, v185, v134
	s_waitcnt lgkmcnt(9)
	v_mfma_f32_32x32x16_bf16 v[80:95], v[176:179], v[116:119], v[80:95]
	v_add_f32_e32 v134, v187, v134
	v_add_f32_e32 v134, v188, v134
	v_add_f32_e32 v134, v189, v134
	v_add_f32_e32 v134, v142, v134
	v_exp_f32_e32 v202, v139
	v_add_f32_e32 v134, v143, v134
	v_exp_f32_e32 v203, v136
	s_waitcnt lgkmcnt(8)
	v_mfma_f32_32x32x16_bf16 v[64:79], v[214:217], v[116:119], v[64:79]
	v_add_f32_e32 v134, v180, v134
	v_exp_f32_e32 v204, v137
	v_add_f32_e32 v134, v181, v134
	v_add_f32_e32 v134, v206, v134
	v_add_f32_e32 v134, v202, v134
	v_add_f32_e32 v134, v203, v134
	v_add_f32_e32 v134, v204, v134
	s_waitcnt lgkmcnt(7)
	v_mfma_f32_32x32x16_bf16 v[80:95], v[218:221], v[108:111], v[80:95]
	v_add_f32_e32 v134, v205, v134
	v_exp_f32_e32 v210, v147
	v_add_f32_e32 v134, v207, v134
	v_exp_f32_e32 v211, v144
	v_add_f32_e32 v134, v148, v134
	v_exp_f32_e32 v212, v145
	v_add_f32_e32 v134, v149, v134
	s_waitcnt lgkmcnt(6)
	v_mfma_f32_32x32x16_bf16 v[64:79], v[222:225], v[108:111], v[64:79]
	v_add_f32_e32 v134, v209, v134
	v_add_f32_e32 v134, v210, v134
	v_add_f32_e32 v134, v211, v134
	v_add_f32_e32 v176, v212, v134
	v_cvt_pk_bf16_f32 v134, v190, v191
	v_cvt_pk_bf16_f32 v136, v194, v196
	s_waitcnt lgkmcnt(5)
	v_mfma_f32_32x32x16_bf16 v[80:95], v[226:229], v[104:107], v[80:95]
	v_cvt_pk_bf16_f32 v137, v195, v197
	v_cvt_pk_bf16_f32 v139, v184, v186
	v_cvt_pk_bf16_f32 v142, v142, v143
	s_waitcnt lgkmcnt(4)
	v_mfma_f32_32x32x16_bf16 v[64:79], v[230:233], v[104:107], v[64:79]
	v_cvt_pk_bf16_f32 v143, v180, v181
	v_cvt_pk_bf16_f32 v144, v206, v202
	v_cvt_pk_bf16_f32 v145, v203, v204
	v_cvt_pk_bf16_f32 v146, v205, v207
	v_cvt_pk_bf16_f32 v147, v148, v149
	v_cvt_pk_bf16_f32 v148, v209, v210
	v_cvt_pk_bf16_f32 v149, v211, v212
	s_waitcnt lgkmcnt(3)
	v_mfma_f32_32x32x16_bf16 v[80:95], v[234:237], v[100:103], v[80:95]
	s_waitcnt lgkmcnt(2)
	v_mfma_f32_32x32x16_bf16 v[64:79], v[238:241], v[100:103], v[64:79]
	s_waitcnt lgkmcnt(1)
	v_mfma_f32_32x32x16_bf16 v[80:95], v[198:201], v[96:99], v[80:95]
	s_waitcnt lgkmcnt(0)
	v_mfma_f32_32x32x16_bf16 v[64:79], v[242:245], v[96:99], v[64:79]
	ds_read_b64_tr_b16 v[196:197], v161 offset:0
	ds_read_b64_tr_b16 v[198:199], v161 offset:0x800
	ds_read_b64_tr_b16 v[200:201], v161 offset:0x1000
	ds_read_b64_tr_b16 v[202:203], v161 offset:0x1800
	ds_read_b64_tr_b16 v[204:205], v161 offset:0x2000
	ds_read_b64_tr_b16 v[206:207], v161 offset:0x2800
	ds_read_b64_tr_b16 v[210:211], v161 offset:0x3000
	ds_read_b64_tr_b16 v[212:213], v161 offset:0x3800
	s_waitcnt lgkmcnt(0)
	s_nop 0
	v_mfma_f32_32x32x16_bf16 v[0:15], v[134:137], v[196:199], v[0:15]
	ds_read_b64_tr_b16 v[196:197], v161 offset:0x200
	ds_read_b64_tr_b16 v[198:199], v161 offset:0xa00
	v_max_f32_e32 v234, v80, v81
	v_max3_f32 v234, v234, v82, v83
	v_max3_f32 v234, v234, v84, v85
	v_max3_f32 v234, v234, v86, v87
	v_max3_f32 v234, v234, v88, v89
	v_mfma_f32_32x32x16_bf16 v[0:15], v[138:141], v[200:203], v[0:15]
	ds_read_b64_tr_b16 v[200:201], v161 offset:0x1200
	ds_read_b64_tr_b16 v[202:203], v161 offset:0x1a00
	v_max3_f32 v234, v234, v90, v91
	v_max3_f32 v234, v234, v92, v93
	v_max3_f32 v234, v234, v94, v95
	v_max3_f32 v234, v234, v64, v65
	v_max3_f32 v234, v234, v66, v67
	v_mfma_f32_32x32x16_bf16 v[0:15], v[142:145], v[204:207], v[0:15]
	ds_read_b64_tr_b16 v[204:205], v161 offset:0x2200
	ds_read_b64_tr_b16 v[206:207], v161 offset:0x2a00
	ds_read_b64_tr_b16 v[214:215], v161 offset:0x3200
	ds_read_b64_tr_b16 v[216:217], v161 offset:0x3a00
	v_max3_f32 v234, v234, v68, v69
	v_max3_f32 v234, v234, v70, v71
	v_max3_f32 v234, v234, v72, v73
	v_max3_f32 v234, v234, v74, v75
	v_max3_f32 v234, v234, v76, v77
	s_waitcnt lgkmcnt(0)
	v_mfma_f32_32x32x16_bf16 v[0:15], v[146:149], v[210:213], v[0:15]
	v_max3_f32 v234, v234, v78, v79
	v_mov_b32_e32 v235, v234
	v_mfma_f32_32x32x16_bf16 v[48:63], v[134:137], v[196:199], v[48:63]
	ds_read_b64_tr_b16 v[196:197], v161 offset:0x400
	ds_read_b64_tr_b16 v[198:199], v161 offset:0xc00
	v_permlane32_swap_b32_e32 v234, v235
	v_max_f32_e32 v234, v234, v235
	v_mfma_f32_32x32x16_bf16 v[48:63], v[138:141], v[200:203], v[48:63]
	ds_read_b64_tr_b16 v[200:201], v161 offset:0x1400
	ds_read_b64_tr_b16 v[202:203], v161 offset:0x1c00
	v_sub_f32_e32 v235, v234, v175
	v_max_f32_e32 v234, v175, v234
	v_sub_f32_e32 v236, v175, v234
	v_mul_f32_e32 v236, 0x3e0293ee, v236
	v_mfma_f32_32x32x16_bf16 v[48:63], v[142:145], v[204:207], v[48:63]
	ds_read_b64_tr_b16 v[204:205], v161 offset:0x2400
	ds_read_b64_tr_b16 v[206:207], v161 offset:0x2c00
	ds_read_b64_tr_b16 v[210:211], v161 offset:0x3400
	ds_read_b64_tr_b16 v[212:213], v161 offset:0x3c00
	v_exp_f32_e32 v236, v236
	v_cmp_ge_f32_e32 vcc, s15, v235
	s_cmp_eq_u64 vcc, exec
	s_cselect_b64 s[8:9], -1, 0
	s_waitcnt lgkmcnt(0)
	v_mfma_f32_32x32x16_bf16 v[48:63], v[146:149], v[214:217], v[48:63]
	v_cndmask_b32_e64 v179, v236, 1.0, s[8:9]
	v_cndmask_b32_e64 v234, v234, v175, s[8:9]
	v_mul_f32_e32 v238, 0xbe0293ee, v234
	v_fmamk_f32 v88, v88, 0x3e0293ee, v238
	v_fmamk_f32 v89, v89, 0x3e0293ee, v238
	v_fmamk_f32 v80, v80, 0x3e0293ee, v238
	v_fmamk_f32 v81, v81, 0x3e0293ee, v238
	v_mfma_f32_32x32x16_bf16 v[32:47], v[134:137], v[196:199], v[32:47]
	ds_read_b64_tr_b16 v[196:197], v161 offset:0x600
	ds_read_b64_tr_b16 v[198:199], v161 offset:0xe00
	v_fmamk_f32 v82, v82, 0x3e0293ee, v238
	v_fmamk_f32 v83, v83, 0x3e0293ee, v238
	v_fmamk_f32 v84, v84, 0x3e0293ee, v238
	v_fmamk_f32 v85, v85, 0x3e0293ee, v238
	v_fmamk_f32 v86, v86, 0x3e0293ee, v238
	v_fmamk_f32 v87, v87, 0x3e0293ee, v238
	v_fmamk_f32 v90, v90, 0x3e0293ee, v238
	v_fmamk_f32 v91, v91, 0x3e0293ee, v238
	v_mfma_f32_32x32x16_bf16 v[32:47], v[138:141], v[200:203], v[32:47]
	ds_read_b64_tr_b16 v[200:201], v161 offset:0x1600
	ds_read_b64_tr_b16 v[202:203], v161 offset:0x1e00
	v_fmamk_f32 v92, v92, 0x3e0293ee, v238
	v_fmamk_f32 v93, v93, 0x3e0293ee, v238
	v_fmamk_f32 v94, v94, 0x3e0293ee, v238
	v_fmamk_f32 v95, v95, 0x3e0293ee, v238
	v_fmamk_f32 v188, v64, 0x3e0293ee, v238
	v_fmamk_f32 v189, v65, 0x3e0293ee, v238
	v_fmamk_f32 v190, v66, 0x3e0293ee, v238
	v_fmamk_f32 v191, v67, 0x3e0293ee, v238
	v_mfma_f32_32x32x16_bf16 v[32:47], v[142:145], v[204:207], v[32:47]
	ds_read_b64_tr_b16 v[204:205], v161 offset:0x2600
	ds_read_b64_tr_b16 v[206:207], v161 offset:0x2e00
	ds_read_b64_tr_b16 v[214:215], v161 offset:0x3600
	ds_read_b64_tr_b16 v[216:217], v161 offset:0x3e00
	v_fmamk_f32 v182, v70, 0x3e0293ee, v238
	v_fmamk_f32 v183, v71, 0x3e0293ee, v238
	v_fmamk_f32 v184, v72, 0x3e0293ee, v238
	v_fmamk_f32 v185, v73, 0x3e0293ee, v238
	v_fmamk_f32 v186, v74, 0x3e0293ee, v238
	v_fmamk_f32 v187, v75, 0x3e0293ee, v238
	s_waitcnt lgkmcnt(0)
	v_mfma_f32_32x32x16_bf16 v[32:47], v[146:149], v[210:213], v[32:47]
	v_fmamk_f32 v192, v68, 0x3e0293ee, v238
	v_fmamk_f32 v181, v69, 0x3e0293ee, v238
	v_fmamk_f32 v180, v76, 0x3e0293ee, v238
	v_mfma_f32_32x32x16_bf16 v[16:31], v[134:137], v[196:199], v[16:31]
	v_fmamk_f32 v193, v77, 0x3e0293ee, v238
	v_fmamk_f32 v194, v78, 0x3e0293ee, v238
	v_fmamk_f32 v177, v79, 0x3e0293ee, v238
	v_mov_b32_e32 v134, v234
	v_exp_f32_e32 v135, v88
	v_exp_f32_e32 v136, v89
	v_exp_f32_e32 v137, v90
	v_mfma_f32_32x32x16_bf16 v[16:31], v[138:141], v[200:203], v[16:31]
	v_exp_f32_e32 v139, v91
	v_exp_f32_e32 v138, v92
	v_exp_f32_e32 v140, v93
	v_exp_f32_e32 v141, v94
	v_mfma_f32_32x32x16_bf16 v[16:31], v[142:145], v[204:207], v[16:31]
	v_exp_f32_e32 v142, v95
	v_exp_f32_e32 v143, v80
	v_exp_f32_e32 v144, v81
	v_exp_f32_e32 v145, v82
	v_mfma_f32_32x32x16_bf16 v[16:31], v[146:149], v[214:217], v[16:31]
	v_exp_f32_e32 v146, v83
	v_exp_f32_e32 v147, v84
	v_exp_f32_e32 v149, v85
	v_exp_f32_e32 v148, v86
	v_exp_f32_e32 v175, v87
	v_cmp_gt_f32_e32 vcc, 1.0, v179
	s_waitcnt vmcnt(0)
	s_barrier
	s_add_u32 m0, s86, 0x0
	s_nop 0
	global_load_lds_dwordx4 v249, s[84:85]
	s_add_u32 m0, s86, 0x380
	s_nop 0
	global_load_lds_dwordx4 v249, s[84:85] offset:128
	s_add_u32 s84, s84, 0x8000
	s_addc_u32 s85, s85, 0
	s_cbranch_vccz .LBB0_437
	s_and_saveexec_b64 s[2:3], s[6:7]
	ds_write_b32 v158, v179 offset:128
	s_or_b64 exec, exec, s[2:3]
	s_waitcnt lgkmcnt(0)
	v_add_u32_e32 v234, v131, v128
	ds_read_b128 v[218:221], v234 offset:224
	ds_read_b128 v[222:225], v234 offset:192
	ds_read_b128 v[226:229], v234 offset:160
	ds_read_b128 v[230:233], v234 offset:128
	s_waitcnt lgkmcnt(3)
	v_pk_mul_f32 v[12:13], v[12:13], v[218:219]
	s_waitcnt lgkmcnt(2)
	v_pk_mul_f32 v[8:9], v[8:9], v[222:223]
	s_waitcnt lgkmcnt(1)
	v_pk_mul_f32 v[4:5], v[4:5], v[226:227]
	v_pk_mul_f32 v[14:15], v[14:15], v[220:221]
	v_pk_mul_f32 v[10:11], v[10:11], v[224:225]
	v_pk_mul_f32 v[6:7], v[6:7], v[228:229]
	s_waitcnt lgkmcnt(0)
	v_pk_mul_f32 v[2:3], v[2:3], v[232:233]
	v_pk_mul_f32 v[0:1], v[0:1], v[230:231]
	v_pk_mul_f32 v[60:61], v[60:61], v[218:219]
	v_pk_mul_f32 v[56:57], v[56:57], v[222:223]
	v_pk_mul_f32 v[52:53], v[52:53], v[226:227]
	v_pk_mul_f32 v[62:63], v[62:63], v[220:221]
	v_pk_mul_f32 v[58:59], v[58:59], v[224:225]
	v_pk_mul_f32 v[54:55], v[54:55], v[228:229]
	v_pk_mul_f32 v[50:51], v[50:51], v[232:233]
	v_pk_mul_f32 v[48:49], v[48:49], v[230:231]
	v_pk_mul_f32 v[44:45], v[44:45], v[218:219]
	v_pk_mul_f32 v[40:41], v[40:41], v[222:223]
	v_pk_mul_f32 v[36:37], v[36:37], v[226:227]
	v_pk_mul_f32 v[46:47], v[46:47], v[220:221]
	v_pk_mul_f32 v[42:43], v[42:43], v[224:225]
	v_pk_mul_f32 v[38:39], v[38:39], v[228:229]
	v_pk_mul_f32 v[34:35], v[34:35], v[232:233]
	v_pk_mul_f32 v[32:33], v[32:33], v[230:231]
	v_pk_mul_f32 v[28:29], v[28:29], v[218:219]
	v_pk_mul_f32 v[24:25], v[24:25], v[222:223]
	v_pk_mul_f32 v[20:21], v[20:21], v[226:227]
	v_pk_mul_f32 v[30:31], v[30:31], v[220:221]
	v_pk_mul_f32 v[26:27], v[26:27], v[224:225]
	v_pk_mul_f32 v[22:23], v[22:23], v[228:229]
	v_pk_mul_f32 v[18:19], v[18:19], v[232:233]
	v_pk_mul_f32 v[16:17], v[16:17], v[230:231]
.LBB0_437:
	s_add_u32 m0, s86, 0xc000
	s_nop 0
	global_load_lds_dwordx4 v247, s[82:83]
	s_add_u32 m0, s86, 0xc400
	s_nop 0
	global_load_lds_dwordx4 v248, s[82:83]
	s_add_u32 s82, s82, 0x8000
	s_addc_u32 s83, s83, 0
	ds_read_b128 v[64:67], v166 offset:32768
	ds_read_b128 v[68:71], v166 offset:40960
	ds_read_b128 v[196:199], v167 offset:32768
	ds_read_b128 v[200:203], v167 offset:40960
	ds_read_b128 v[204:207], v168 offset:32768
	ds_read_b128 v[210:213], v168 offset:40960
	v_exp_f32_e32 v188, v188
	v_exp_f32_e32 v189, v189
	s_waitcnt lgkmcnt(5)
	v_mfma_f32_32x32x16_bf16 v[80:95], v[64:67], v[124:127], 0
	v_exp_f32_e32 v190, v190
	v_exp_f32_e32 v191, v191
	v_exp_f32_e32 v192, v192
	v_exp_f32_e32 v195, v181
	v_exp_f32_e32 v182, v182
	v_exp_f32_e32 v183, v183
	v_exp_f32_e32 v184, v184
	s_waitcnt lgkmcnt(4)
	v_mfma_f32_32x32x16_bf16 v[64:79], v[68:71], v[124:127], 0
	v_exp_f32_e32 v185, v185
	v_exp_f32_e32 v186, v186
	v_exp_f32_e32 v187, v187
	v_exp_f32_e32 v193, v193
	v_exp_f32_e32 v194, v194
	v_exp_f32_e32 v177, v177
	s_waitcnt lgkmcnt(3)
	v_mfma_f32_32x32x16_bf16 v[80:95], v[196:199], v[120:123], v[80:95]
	ds_read_b128 v[196:199], v169 offset:32768
	ds_read_b128 v[214:217], v169 offset:40960
	ds_read_b128 v[218:221], v170 offset:32768
	ds_read_b128 v[222:225], v170 offset:40960
	ds_read_b128 v[226:229], v171 offset:32768
	ds_read_b128 v[230:233], v171 offset:40960
	ds_read_b128 v[234:237], v172 offset:32768
	ds_read_b128 v[238:241], v172 offset:40960
	s_waitcnt lgkmcnt(10)
	v_mfma_f32_32x32x16_bf16 v[64:79], v[200:203], v[120:123], v[64:79]
	ds_read_b128 v[200:203], v173 offset:32768
	ds_read_b128 v[242:245], v173 offset:40960
	s_waitcnt lgkmcnt(11)
	v_mfma_f32_32x32x16_bf16 v[80:95], v[204:207], v[112:115], v[80:95]
	v_exp_f32_e32 v204, v180
	v_add_f32_e32 v180, v144, v143
	v_add_f32_e32 v180, v145, v180
	v_add_f32_e32 v180, v146, v180
	v_add_f32_e32 v180, v147, v180
	v_add_f32_e32 v180, v149, v180
	s_waitcnt lgkmcnt(10)
	v_mfma_f32_32x32x16_bf16 v[64:79], v[210:213], v[112:115], v[64:79]
	v_add_f32_e32 v180, v148, v180
	v_add_f32_e32 v180, v175, v180
	v_add_f32_e32 v180, v135, v180
	v_add_f32_e32 v180, v136, v180
	v_add_f32_e32 v180, v137, v180
	v_add_f32_e32 v180, v139, v180
	v_add_f32_e32 v180, v138, v180
	s_waitcnt lgkmcnt(9)
	v_mfma_f32_32x32x16_bf16 v[80:95], v[196:199], v[116:119], v[80:95]
	v_add_f32_e32 v180, v140, v180
	v_add_f32_e32 v180, v141, v180
	v_add_f32_e32 v180, v142, v180
	v_add_f32_e32 v180, v188, v180
	v_add_f32_e32 v180, v189, v180
	v_add_f32_e32 v180, v190, v180
	v_add_f32_e32 v180, v191, v180
	s_waitcnt lgkmcnt(8)
	v_mfma_f32_32x32x16_bf16 v[64:79], v[214:217], v[116:119], v[64:79]
	v_add_f32_e32 v180, v192, v180
	v_add_f32_e32 v180, v195, v180
	v_add_f32_e32 v180, v182, v180
	v_add_f32_e32 v180, v183, v180
	v_add_f32_e32 v180, v184, v180
	v_add_f32_e32 v180, v185, v180
	v_add_f32_e32 v180, v186, v180
	s_waitcnt lgkmcnt(7)
	v_mfma_f32_32x32x16_bf16 v[80:95], v[218:221], v[108:111], v[80:95]
	v_add_f32_e32 v180, v187, v180
	v_add_f32_e32 v180, v204, v180
	v_add_f32_e32 v180, v193, v180
	v_add_f32_e32 v180, v194, v180
	v_add_f32_e32 v180, v177, v180
	s_waitcnt lgkmcnt(6)
	v_mfma_f32_32x32x16_bf16 v[64:79], v[222:225], v[108:111], v[64:79]
	v_cvt_pk_bf16_f32 v144, v143, v144
	v_cvt_pk_bf16_f32 v145, v145, v146
	v_cvt_pk_bf16_f32 v146, v147, v149
	v_cvt_pk_bf16_f32 v147, v148, v175
	v_cvt_pk_bf16_f32 v136, v135, v136
	v_cvt_pk_bf16_f32 v137, v137, v139
	v_cvt_pk_bf16_f32 v138, v138, v140
	s_waitcnt lgkmcnt(5)
	v_mfma_f32_32x32x16_bf16 v[80:95], v[226:229], v[104:107], v[80:95]
	v_cvt_pk_bf16_f32 v139, v141, v142
	v_cvt_pk_bf16_f32 v140, v188, v189
	v_cvt_pk_bf16_f32 v141, v190, v191
	v_cvt_pk_bf16_f32 v142, v192, v195
	v_cvt_pk_bf16_f32 v143, v182, v183
	v_cvt_pk_bf16_f32 v182, v184, v185
	v_cvt_pk_bf16_f32 v183, v186, v187
	s_waitcnt lgkmcnt(4)
	v_mfma_f32_32x32x16_bf16 v[64:79], v[230:233], v[104:107], v[64:79]
	v_cvt_pk_bf16_f32 v184, v204, v193
	v_cvt_pk_bf16_f32 v185, v194, v177
	s_waitcnt lgkmcnt(3)
	v_mfma_f32_32x32x16_bf16 v[80:95], v[234:237], v[100:103], v[80:95]
	s_waitcnt lgkmcnt(2)
	v_mfma_f32_32x32x16_bf16 v[64:79], v[238:241], v[100:103], v[64:79]
	s_waitcnt lgkmcnt(1)
	v_mfma_f32_32x32x16_bf16 v[80:95], v[200:203], v[96:99], v[80:95]
	s_waitcnt lgkmcnt(0)
	v_mfma_f32_32x32x16_bf16 v[64:79], v[242:245], v[96:99], v[64:79]
	ds_read_b64_tr_b16 v[202:203], v160 offset:0
	ds_read_b64_tr_b16 v[204:205], v160 offset:0x800
	ds_read_b64_tr_b16 v[210:211], v160 offset:0x1000
	ds_read_b64_tr_b16 v[212:213], v160 offset:0x1800
	ds_read_b64_tr_b16 v[214:215], v160 offset:0x2000
	ds_read_b64_tr_b16 v[216:217], v160 offset:0x2800
	ds_read_b64_tr_b16 v[218:219], v160 offset:0x3000
	ds_read_b64_tr_b16 v[220:221], v160 offset:0x3800
	s_waitcnt lgkmcnt(0)
	s_nop 0
	v_mfma_f32_32x32x16_bf16 v[0:15], v[144:147], v[202:205], v[0:15]
	ds_read_b64_tr_b16 v[202:203], v160 offset:0x200
	ds_read_b64_tr_b16 v[204:205], v160 offset:0xa00
	v_max_f32_e32 v242, v80, v81
	v_max3_f32 v242, v242, v82, v83
	v_max3_f32 v242, v242, v84, v85
	v_max3_f32 v242, v242, v86, v87
	v_max3_f32 v242, v242, v88, v89
	v_mfma_f32_32x32x16_bf16 v[0:15], v[136:139], v[210:213], v[0:15]
	ds_read_b64_tr_b16 v[210:211], v160 offset:0x1200
	ds_read_b64_tr_b16 v[212:213], v160 offset:0x1a00
	v_max3_f32 v242, v242, v90, v91
	v_max3_f32 v242, v242, v92, v93
	v_max3_f32 v242, v242, v94, v95
	v_max3_f32 v242, v242, v64, v65
	v_max3_f32 v242, v242, v66, v67
	v_mfma_f32_32x32x16_bf16 v[0:15], v[140:143], v[214:217], v[0:15]
	ds_read_b64_tr_b16 v[214:215], v160 offset:0x2200
	ds_read_b64_tr_b16 v[216:217], v160 offset:0x2a00
	ds_read_b64_tr_b16 v[222:223], v160 offset:0x3200
	ds_read_b64_tr_b16 v[224:225], v160 offset:0x3a00
	v_max3_f32 v242, v242, v68, v69
	v_max3_f32 v242, v242, v70, v71
	v_max3_f32 v242, v242, v72, v73
	v_max3_f32 v242, v242, v74, v75
	v_max3_f32 v242, v242, v76, v77
	s_waitcnt lgkmcnt(0)
	v_mfma_f32_32x32x16_bf16 v[0:15], v[182:185], v[218:221], v[0:15]
	v_max3_f32 v242, v242, v78, v79
	v_mov_b32_e32 v243, v242
	v_mfma_f32_32x32x16_bf16 v[48:63], v[144:147], v[202:205], v[48:63]
	ds_read_b64_tr_b16 v[202:203], v160 offset:0x400
	ds_read_b64_tr_b16 v[204:205], v160 offset:0xc00
	v_permlane32_swap_b32_e32 v242, v243
	v_max_f32_e32 v242, v242, v243
	v_mfma_f32_32x32x16_bf16 v[48:63], v[136:139], v[210:213], v[48:63]
	ds_read_b64_tr_b16 v[210:211], v160 offset:0x1400
	ds_read_b64_tr_b16 v[212:213], v160 offset:0x1c00
	v_sub_f32_e32 v243, v242, v134
	v_max_f32_e32 v242, v134, v242
	v_sub_f32_e32 v148, v134, v242
	v_mul_f32_e32 v148, 0x3e0293ee, v148
	v_mfma_f32_32x32x16_bf16 v[48:63], v[140:143], v[214:217], v[48:63]
	ds_read_b64_tr_b16 v[214:215], v160 offset:0x2400
	ds_read_b64_tr_b16 v[216:217], v160 offset:0x2c00
	ds_read_b64_tr_b16 v[218:219], v160 offset:0x3400
	ds_read_b64_tr_b16 v[220:221], v160 offset:0x3c00
	v_exp_f32_e32 v148, v148
	v_cmp_ge_f32_e32 vcc, s15, v243
	s_cmp_eq_u64 vcc, exec
	s_cselect_b64 s[8:9], -1, 0
	s_waitcnt lgkmcnt(0)
	v_mfma_f32_32x32x16_bf16 v[48:63], v[182:185], v[222:225], v[48:63]
	v_cndmask_b32_e64 v177, v148, 1.0, s[8:9]
	v_cndmask_b32_e64 v175, v242, v134, s[8:9]
	v_mul_f32_e32 v244, 0xbe0293ee, v175
	v_fmamk_f32 v80, v80, 0x3e0293ee, v244
	v_fmamk_f32 v81, v81, 0x3e0293ee, v244
	v_fmamk_f32 v82, v82, 0x3e0293ee, v244
	v_fmamk_f32 v83, v83, 0x3e0293ee, v244
	v_mfma_f32_32x32x16_bf16 v[32:47], v[144:147], v[202:205], v[32:47]
	ds_read_b64_tr_b16 v[202:203], v160 offset:0x600
	ds_read_b64_tr_b16 v[204:205], v160 offset:0xe00
	v_fmamk_f32 v84, v84, 0x3e0293ee, v244
	v_fmamk_f32 v85, v85, 0x3e0293ee, v244
	v_fmamk_f32 v86, v86, 0x3e0293ee, v244
	v_fmamk_f32 v87, v87, 0x3e0293ee, v244
	v_fmamk_f32 v88, v88, 0x3e0293ee, v244
	v_fmamk_f32 v89, v89, 0x3e0293ee, v244
	v_fmamk_f32 v90, v90, 0x3e0293ee, v244
	v_fmamk_f32 v91, v91, 0x3e0293ee, v244
	v_mfma_f32_32x32x16_bf16 v[32:47], v[136:139], v[210:213], v[32:47]
	ds_read_b64_tr_b16 v[210:211], v160 offset:0x1600
	ds_read_b64_tr_b16 v[212:213], v160 offset:0x1e00
	v_fmamk_f32 v92, v92, 0x3e0293ee, v244
	v_fmamk_f32 v93, v93, 0x3e0293ee, v244
	v_fmamk_f32 v94, v94, 0x3e0293ee, v244
	v_fmamk_f32 v95, v95, 0x3e0293ee, v244
	v_fmamk_f32 v134, v72, 0x3e0293ee, v244
	v_fmamk_f32 v135, v73, 0x3e0293ee, v244
	v_fmamk_f32 v148, v74, 0x3e0293ee, v244
	v_fmamk_f32 v149, v75, 0x3e0293ee, v244
	v_mfma_f32_32x32x16_bf16 v[32:47], v[140:143], v[214:217], v[32:47]
	ds_read_b64_tr_b16 v[214:215], v160 offset:0x2600
	ds_read_b64_tr_b16 v[216:217], v160 offset:0x2e00
	ds_read_b64_tr_b16 v[222:223], v160 offset:0x3600
	ds_read_b64_tr_b16 v[224:225], v160 offset:0x3e00
	v_exp_f32_e32 v190, v80
	v_exp_f32_e32 v191, v81
	v_exp_f32_e32 v192, v82
	s_waitcnt lgkmcnt(0)
	v_mfma_f32_32x32x16_bf16 v[32:47], v[182:185], v[218:221], v[32:47]
	v_exp_f32_e32 v193, v83
	v_exp_f32_e32 v194, v84
	v_exp_f32_e32 v196, v85
	v_mfma_f32_32x32x16_bf16 v[16:31], v[144:147], v[202:205], v[16:31]
	v_fmamk_f32 v144, v78, 0x3e0293ee, v244
	v_fmamk_f32 v145, v79, 0x3e0293ee, v244
	v_fmamk_f32 v146, v76, 0x3e0293ee, v244
	v_fmamk_f32 v147, v77, 0x3e0293ee, v244
	v_exp_f32_e32 v195, v86
	v_exp_f32_e32 v197, v87
	v_mfma_f32_32x32x16_bf16 v[16:31], v[136:139], v[210:213], v[16:31]
	v_fmamk_f32 v136, v70, 0x3e0293ee, v244
	v_fmamk_f32 v137, v71, 0x3e0293ee, v244
	v_fmamk_f32 v138, v68, 0x3e0293ee, v244
	v_fmamk_f32 v139, v69, 0x3e0293ee, v244
	v_exp_f32_e32 v186, v91
	v_exp_f32_e32 v187, v93
	v_mfma_f32_32x32x16_bf16 v[16:31], v[140:143], v[214:217], v[16:31]
	v_fmamk_f32 v140, v66, 0x3e0293ee, v244
	v_fmamk_f32 v141, v67, 0x3e0293ee, v244
	v_fmamk_f32 v142, v64, 0x3e0293ee, v244
	v_fmamk_f32 v143, v65, 0x3e0293ee, v244
	v_exp_f32_e32 v188, v94
	v_exp_f32_e32 v189, v95
	v_mfma_f32_32x32x16_bf16 v[16:31], v[182:185], v[222:225], v[16:31]
	v_exp_f32_e32 v182, v88
	v_exp_f32_e32 v183, v89
	v_exp_f32_e32 v184, v90
	v_exp_f32_e32 v185, v92
	v_cmp_gt_f32_e32 vcc, 1.0, v177
	s_waitcnt vmcnt(0)
	s_barrier
	s_add_u32 m0, s86, 0x4000
	s_nop 0
	global_load_lds_dwordx4 v249, s[84:85]
	s_add_u32 m0, s86, 0x4380
	s_nop 0
	global_load_lds_dwordx4 v249, s[84:85] offset:128
	s_add_u32 s84, s84, 0x8000
	s_addc_u32 s85, s85, 0
	s_cbranch_vccz .LBB0_441
	s_and_saveexec_b64 s[2:3], s[6:7]
	ds_write_b32 v158, v177 offset:128
	s_or_b64 exec, exec, s[2:3]
	s_waitcnt lgkmcnt(0)
	v_add_u32_e32 v242, v131, v128
	ds_read_b128 v[226:229], v242 offset:224
	ds_read_b128 v[230:233], v242 offset:192
	ds_read_b128 v[234:237], v242 offset:160
	ds_read_b128 v[238:241], v242 offset:128
	s_waitcnt lgkmcnt(3)
	v_pk_mul_f32 v[12:13], v[12:13], v[226:227]
	s_waitcnt lgkmcnt(2)
	v_pk_mul_f32 v[8:9], v[8:9], v[230:231]
	s_waitcnt lgkmcnt(1)
	v_pk_mul_f32 v[4:5], v[4:5], v[234:235]
	v_pk_mul_f32 v[14:15], v[14:15], v[228:229]
	v_pk_mul_f32 v[10:11], v[10:11], v[232:233]
	v_pk_mul_f32 v[6:7], v[6:7], v[236:237]
	s_waitcnt lgkmcnt(0)
	v_pk_mul_f32 v[2:3], v[2:3], v[240:241]
	v_pk_mul_f32 v[0:1], v[0:1], v[238:239]
	v_pk_mul_f32 v[60:61], v[60:61], v[226:227]
	v_pk_mul_f32 v[56:57], v[56:57], v[230:231]
	v_pk_mul_f32 v[52:53], v[52:53], v[234:235]
	v_pk_mul_f32 v[62:63], v[62:63], v[228:229]
	v_pk_mul_f32 v[58:59], v[58:59], v[232:233]
	v_pk_mul_f32 v[54:55], v[54:55], v[236:237]
	v_pk_mul_f32 v[50:51], v[50:51], v[240:241]
	v_pk_mul_f32 v[48:49], v[48:49], v[238:239]
	v_pk_mul_f32 v[44:45], v[44:45], v[226:227]
	v_pk_mul_f32 v[40:41], v[40:41], v[230:231]
	v_pk_mul_f32 v[36:37], v[36:37], v[234:235]
	v_pk_mul_f32 v[46:47], v[46:47], v[228:229]
	v_pk_mul_f32 v[42:43], v[42:43], v[232:233]
	v_pk_mul_f32 v[38:39], v[38:39], v[236:237]
	v_pk_mul_f32 v[34:35], v[34:35], v[240:241]
	v_pk_mul_f32 v[32:33], v[32:33], v[238:239]
	v_pk_mul_f32 v[28:29], v[28:29], v[226:227]
	v_pk_mul_f32 v[24:25], v[24:25], v[230:231]
	v_pk_mul_f32 v[20:21], v[20:21], v[234:235]
	v_pk_mul_f32 v[30:31], v[30:31], v[228:229]
	v_pk_mul_f32 v[26:27], v[26:27], v[232:233]
	v_pk_mul_f32 v[22:23], v[22:23], v[236:237]
	v_pk_mul_f32 v[18:19], v[18:19], v[240:241]
	v_pk_mul_f32 v[16:17], v[16:17], v[238:239]
.LBB0_441:
	v_fma_f32 v64, v174, v159, v176
	s_add_i32 s68, s68, 2
	v_fma_f32 v159, v64, v179, v180
	s_cmp_gt_u32 s68, 32
	s_cbranch_scc1 .LBB0_443
	v_mov_b32_e32 v174, v177
	s_branch .LBB0_433
.LBB0_443:
	v_mov_b32_e32 v178, v159
	s_nop 1
	v_permlane32_swap_b32_e32 v159, v178
	v_add_f32_e32 v159, v159, v178
	v_readfirstlane_b32 s85, v155
	v_lshlrev_b32_e32 v230, 2, v157
	s_lshl_b64 s[82:83], s[26:27], 12
	s_add_u32 s82, s61, s82
	s_addc_u32 s83, s62, s83
	s_lshl_b32 s84, s63, 1
	s_add_u32 s82, s82, s84
	s_addc_u32 s83, s83, 0
	s_lshl_b32 s84, s85, 17
	s_add_u32 s82, s82, s84
	s_addc_u32 s83, s83, 0
	s_mul_i32 s84, s85, 0x2200
	s_add_u32 s84, s84, 0x12000
	s_add_u32 m0, s84, 0x0
	s_nop 0
	global_load_lds_dword v230, s[82:83]
	s_add_u32 s82, s82, 0x1000
	s_addc_u32 s83, s83, 0
	s_add_u32 m0, s84, 0x110
	s_nop 0
	global_load_lds_dword v230, s[82:83]
	s_add_u32 s82, s82, 0x1000
	s_addc_u32 s83, s83, 0
	s_add_u32 m0, s84, 0x220
	s_nop 0
	global_load_lds_dword v230, s[82:83]
	s_add_u32 s82, s82, 0x1000
	s_addc_u32 s83, s83, 0
	s_add_u32 m0, s84, 0x330
	s_nop 0
	global_load_lds_dword v230, s[82:83]
	s_add_u32 s82, s82, 0x1000
	s_addc_u32 s83, s83, 0
	s_add_u32 m0, s84, 0x440
	s_nop 0
	global_load_lds_dword v230, s[82:83]
	s_add_u32 s82, s82, 0x1000
	s_addc_u32 s83, s83, 0
	s_add_u32 m0, s84, 0x550
	s_nop 0
	global_load_lds_dword v230, s[82:83]
	s_add_u32 s82, s82, 0x1000
	s_addc_u32 s83, s83, 0
	s_add_u32 m0, s84, 0x660
	s_nop 0
	global_load_lds_dword v230, s[82:83]
	s_add_u32 s82, s82, 0x1000
	s_addc_u32 s83, s83, 0
	s_add_u32 m0, s84, 0x770
	s_nop 0
	global_load_lds_dword v230, s[82:83]
	s_add_u32 s82, s82, 0x1000
	s_addc_u32 s83, s83, 0
	s_add_u32 m0, s84, 0x880
	s_nop 0
	global_load_lds_dword v230, s[82:83]
	s_add_u32 s82, s82, 0x1000
	s_addc_u32 s83, s83, 0
	s_add_u32 m0, s84, 0x990
	s_nop 0
	global_load_lds_dword v230, s[82:83]
	s_add_u32 s82, s82, 0x1000
	s_addc_u32 s83, s83, 0
	s_add_u32 m0, s84, 0xaa0
	s_nop 0
	global_load_lds_dword v230, s[82:83]
	s_add_u32 s82, s82, 0x1000
	s_addc_u32 s83, s83, 0
	s_add_u32 m0, s84, 0xbb0
	s_nop 0
	global_load_lds_dword v230, s[82:83]
	s_add_u32 s82, s82, 0x1000
	s_addc_u32 s83, s83, 0
	s_add_u32 m0, s84, 0xcc0
	s_nop 0
	global_load_lds_dword v230, s[82:83]
	s_add_u32 s82, s82, 0x1000
	s_addc_u32 s83, s83, 0
	s_add_u32 m0, s84, 0xdd0
	s_nop 0
	global_load_lds_dword v230, s[82:83]
	s_add_u32 s82, s82, 0x1000
	s_addc_u32 s83, s83, 0
	s_add_u32 m0, s84, 0xee0
	s_nop 0
	global_load_lds_dword v230, s[82:83]
	s_add_u32 s82, s82, 0x1000
	s_addc_u32 s83, s83, 0
	s_add_u32 m0, s84, 0xff0
	s_nop 0
	global_load_lds_dword v230, s[82:83]
	s_add_u32 s82, s82, 0x1000
	s_addc_u32 s83, s83, 0
	s_add_u32 m0, s84, 0x1100
	s_nop 0
	global_load_lds_dword v230, s[82:83]
	s_add_u32 s82, s82, 0x1000
	s_addc_u32 s83, s83, 0
	s_add_u32 m0, s84, 0x1210
	s_nop 0
	global_load_lds_dword v230, s[82:83]
	s_add_u32 s82, s82, 0x1000
	s_addc_u32 s83, s83, 0
	s_add_u32 m0, s84, 0x1320
	s_nop 0
	global_load_lds_dword v230, s[82:83]
	s_add_u32 s82, s82, 0x1000
	s_addc_u32 s83, s83, 0
	s_add_u32 m0, s84, 0x1430
	s_nop 0
	global_load_lds_dword v230, s[82:83]
	s_add_u32 s82, s82, 0x1000
	s_addc_u32 s83, s83, 0
	s_add_u32 m0, s84, 0x1540
	s_nop 0
	global_load_lds_dword v230, s[82:83]
	s_add_u32 s82, s82, 0x1000
	s_addc_u32 s83, s83, 0
	s_add_u32 m0, s84, 0x1650
	s_nop 0
	global_load_lds_dword v230, s[82:83]
	s_add_u32 s82, s82, 0x1000
	s_addc_u32 s83, s83, 0
	s_add_u32 m0, s84, 0x1760
	s_nop 0
	global_load_lds_dword v230, s[82:83]
	s_add_u32 s82, s82, 0x1000
	s_addc_u32 s83, s83, 0
	s_add_u32 m0, s84, 0x1870
	s_nop 0
	global_load_lds_dword v230, s[82:83]
	s_add_u32 s82, s82, 0x1000
	s_addc_u32 s83, s83, 0
	s_add_u32 m0, s84, 0x1980
	s_nop 0
	global_load_lds_dword v230, s[82:83]
	s_add_u32 s82, s82, 0x1000
	s_addc_u32 s83, s83, 0
	s_add_u32 m0, s84, 0x1a90
	s_nop 0
	global_load_lds_dword v230, s[82:83]
	s_add_u32 s82, s82, 0x1000
	s_addc_u32 s83, s83, 0
	s_add_u32 m0, s84, 0x1ba0
	s_nop 0
	global_load_lds_dword v230, s[82:83]
	s_add_u32 s82, s82, 0x1000
	s_addc_u32 s83, s83, 0
	s_add_u32 m0, s84, 0x1cb0
	s_nop 0
	global_load_lds_dword v230, s[82:83]
	s_add_u32 s82, s82, 0x1000
	s_addc_u32 s83, s83, 0
	s_add_u32 m0, s84, 0x1dc0
	s_nop 0
	global_load_lds_dword v230, s[82:83]
	s_add_u32 s82, s82, 0x1000
	s_addc_u32 s83, s83, 0
	s_add_u32 m0, s84, 0x1ed0
	s_nop 0
	global_load_lds_dword v230, s[82:83]
	s_add_u32 s82, s82, 0x1000
	s_addc_u32 s83, s83, 0
	s_add_u32 m0, s84, 0x1fe0
	s_nop 0
	global_load_lds_dword v230, s[82:83]
	s_add_u32 s82, s82, 0x1000
	s_addc_u32 s83, s83, 0
	s_add_u32 m0, s84, 0x20f0
	s_nop 0
	global_load_lds_dword v230, s[82:83]
	ds_read_b128 v[64:67], v166 offset:49152
	ds_read_b128 v[68:71], v166 offset:57344
	v_exp_f32_e32 v132, v142
	v_exp_f32_e32 v133, v143
	v_exp_f32_e32 v140, v140
	s_waitcnt lgkmcnt(1)
	v_mfma_f32_32x32x16_bf16 v[80:95], v[64:67], v[124:127], 0
	v_exp_f32_e32 v141, v141
	v_exp_f32_e32 v138, v138
	v_exp_f32_e32 v139, v139
	v_exp_f32_e32 v136, v136
	v_exp_f32_e32 v137, v137
	v_exp_f32_e32 v134, v134
	v_exp_f32_e32 v135, v135
	s_waitcnt lgkmcnt(0)
	v_mfma_f32_32x32x16_bf16 v[64:79], v[68:71], v[124:127], 0
	ds_read_b128 v[124:127], v167 offset:49152
	ds_read_b128 v[162:165], v167 offset:57344
	ds_read_b128 v[178:181], v168 offset:49152
	ds_read_b128 v[198:201], v168 offset:57344
	v_exp_f32_e32 v142, v148
	v_exp_f32_e32 v143, v149
	v_exp_f32_e32 v146, v146
	v_exp_f32_e32 v147, v147
	v_exp_f32_e32 v144, v144
	v_exp_f32_e32 v145, v145
	s_waitcnt lgkmcnt(3)
	v_mfma_f32_32x32x16_bf16 v[80:95], v[124:127], v[120:123], v[80:95]
	ds_read_b128 v[124:127], v169 offset:49152
	ds_read_b128 v[166:169], v169 offset:57344
	ds_read_b128 v[202:205], v170 offset:49152
	ds_read_b128 v[210:213], v170 offset:57344
	ds_read_b128 v[214:217], v171 offset:49152
	ds_read_b128 v[218:221], v171 offset:57344
	ds_read_b128 v[222:225], v172 offset:49152
	ds_read_b128 v[226:229], v172 offset:57344
	s_waitcnt lgkmcnt(10)
	v_mfma_f32_32x32x16_bf16 v[64:79], v[162:165], v[120:123], v[64:79]
	ds_read_b128 v[120:123], v173 offset:49152
	ds_read_b128 v[162:165], v173 offset:57344
	s_waitcnt lgkmcnt(11)
	v_mfma_f32_32x32x16_bf16 v[80:95], v[178:181], v[112:115], v[80:95]
	s_waitcnt lgkmcnt(10)
	v_mfma_f32_32x32x16_bf16 v[64:79], v[198:201], v[112:115], v[64:79]
	v_add_f32_e32 v112, 0, v190
	v_add_f32_e32 v112, v191, v112
	v_add_f32_e32 v112, v192, v112
	v_add_f32_e32 v112, v193, v112
	v_add_f32_e32 v112, v194, v112
	v_add_f32_e32 v112, v196, v112
	v_add_f32_e32 v112, v195, v112
	s_waitcnt lgkmcnt(9)
	v_mfma_f32_32x32x16_bf16 v[80:95], v[124:127], v[116:119], v[80:95]
	v_add_f32_e32 v112, v197, v112
	v_add_f32_e32 v112, v182, v112
	v_add_f32_e32 v112, v183, v112
	v_add_f32_e32 v112, v184, v112
	v_add_f32_e32 v112, v186, v112
	v_add_f32_e32 v112, v185, v112
	v_add_f32_e32 v112, v187, v112
	s_waitcnt lgkmcnt(8)
	v_mfma_f32_32x32x16_bf16 v[64:79], v[166:169], v[116:119], v[64:79]
	v_add_f32_e32 v112, v188, v112
	v_add_f32_e32 v112, v189, v112
	v_add_f32_e32 v112, v132, v112
	v_add_f32_e32 v112, v133, v112
	v_add_f32_e32 v112, v140, v112
	v_add_f32_e32 v112, v141, v112
	v_add_f32_e32 v112, v138, v112
	s_waitcnt lgkmcnt(7)
	v_mfma_f32_32x32x16_bf16 v[80:95], v[202:205], v[108:111], v[80:95]
	v_add_f32_e32 v112, v139, v112
	v_add_f32_e32 v112, v136, v112
	v_add_f32_e32 v112, v137, v112
	v_cvt_pk_bf16_f32 v113, v195, v197
	v_cvt_pk_bf16_f32 v114, v132, v133
	v_cvt_pk_bf16_f32 v115, v140, v141
	v_cvt_pk_bf16_f32 v116, v138, v139
	s_waitcnt lgkmcnt(6)
	v_mfma_f32_32x32x16_bf16 v[64:79], v[210:213], v[108:111], v[64:79]
	v_add_f32_e32 v108, v134, v112
	v_add_f32_e32 v108, v135, v108
	v_add_f32_e32 v108, v142, v108
	v_add_f32_e32 v108, v143, v108
	v_add_f32_e32 v108, v146, v108
	v_add_f32_e32 v108, v147, v108
	v_add_f32_e32 v108, v144, v108
	s_waitcnt lgkmcnt(5)
	v_mfma_f32_32x32x16_bf16 v[80:95], v[214:217], v[104:107], v[80:95]
	v_add_f32_e32 v108, v145, v108
	v_mov_b32_e32 v109, v108
	s_nop 1
	v_permlane32_swap_b32_e32 v108, v109
	v_cvt_pk_bf16_f32 v110, v190, v191
	v_cvt_pk_bf16_f32 v111, v192, v193
	v_cvt_pk_bf16_f32 v112, v194, v196
	s_waitcnt lgkmcnt(4)
	v_mfma_f32_32x32x16_bf16 v[64:79], v[218:221], v[104:107], v[64:79]
	v_cvt_pk_bf16_f32 v104, v182, v183
	v_cvt_pk_bf16_f32 v105, v184, v186
	v_cvt_pk_bf16_f32 v106, v185, v187
	v_cvt_pk_bf16_f32 v107, v188, v189
	v_cvt_pk_bf16_f32 v117, v136, v137
	s_waitcnt lgkmcnt(3)
	v_mfma_f32_32x32x16_bf16 v[80:95], v[222:225], v[100:103], v[80:95]
	s_waitcnt lgkmcnt(2)
	v_mfma_f32_32x32x16_bf16 v[64:79], v[226:229], v[100:103], v[64:79]
	v_cvt_pk_bf16_f32 v100, v134, v135
	v_cvt_pk_bf16_f32 v101, v142, v143
	v_cvt_pk_bf16_f32 v102, v146, v147
	v_cvt_pk_bf16_f32 v103, v144, v145
	s_waitcnt lgkmcnt(1)
	v_mfma_f32_32x32x16_bf16 v[80:95], v[120:123], v[96:99], v[80:95]
	s_waitcnt lgkmcnt(0)
	v_mfma_f32_32x32x16_bf16 v[64:79], v[162:165], v[96:99], v[64:79]
	ds_read_b64_tr_b16 v[96:97], v161 offset:0
	ds_read_b64_tr_b16 v[98:99], v161 offset:0x800
	ds_read_b64_tr_b16 v[118:119], v161 offset:0x1000
	ds_read_b64_tr_b16 v[120:121], v161 offset:0x1800
	ds_read_b64_tr_b16 v[122:123], v161 offset:0x2000
	ds_read_b64_tr_b16 v[124:125], v161 offset:0x2800
	ds_read_b64_tr_b16 v[132:133], v161 offset:0x3000
	ds_read_b64_tr_b16 v[134:135], v161 offset:0x3800
	s_waitcnt lgkmcnt(0)
	s_nop 0
	v_mfma_f32_32x32x16_bf16 v[0:15], v[110:113], v[96:99], v[0:15]
	ds_read_b64_tr_b16 v[96:97], v161 offset:0x200
	ds_read_b64_tr_b16 v[98:99], v161 offset:0xa00
	v_mfma_f32_32x32x16_bf16 v[0:15], v[104:107], v[118:121], v[0:15]
	ds_read_b64_tr_b16 v[118:119], v161 offset:0x1200
	ds_read_b64_tr_b16 v[120:121], v161 offset:0x1a00
	v_mfma_f32_32x32x16_bf16 v[0:15], v[114:117], v[122:125], v[0:15]
	ds_read_b64_tr_b16 v[122:123], v161 offset:0x2200
	ds_read_b64_tr_b16 v[124:125], v161 offset:0x2a00
	ds_read_b64_tr_b16 v[136:137], v161 offset:0x3200
	ds_read_b64_tr_b16 v[138:139], v161 offset:0x3a00
	s_waitcnt lgkmcnt(0)
	v_mfma_f32_32x32x16_bf16 v[0:15], v[100:103], v[132:135], v[0:15]
	v_mfma_f32_32x32x16_bf16 v[48:63], v[110:113], v[96:99], v[48:63]
	ds_read_b64_tr_b16 v[96:97], v161 offset:0x400
	ds_read_b64_tr_b16 v[98:99], v161 offset:0xc00
	v_mfma_f32_32x32x16_bf16 v[48:63], v[104:107], v[118:121], v[48:63]
	ds_read_b64_tr_b16 v[118:119], v161 offset:0x1400
	ds_read_b64_tr_b16 v[120:121], v161 offset:0x1c00
	v_mfma_f32_32x32x16_bf16 v[48:63], v[114:117], v[122:125], v[48:63]
	ds_read_b64_tr_b16 v[122:123], v161 offset:0x2400
	ds_read_b64_tr_b16 v[124:125], v161 offset:0x2c00
	ds_read_b64_tr_b16 v[132:133], v161 offset:0x3400
	ds_read_b64_tr_b16 v[134:135], v161 offset:0x3c00
	s_waitcnt lgkmcnt(0)
	v_mfma_f32_32x32x16_bf16 v[48:63], v[100:103], v[136:139], v[48:63]
	v_mfma_f32_32x32x16_bf16 v[32:47], v[110:113], v[96:99], v[32:47]
	ds_read_b64_tr_b16 v[96:97], v161 offset:0x600
	ds_read_b64_tr_b16 v[98:99], v161 offset:0xe00
	v_mfma_f32_32x32x16_bf16 v[32:47], v[104:107], v[118:121], v[32:47]
	ds_read_b64_tr_b16 v[118:119], v161 offset:0x1600
	ds_read_b64_tr_b16 v[120:121], v161 offset:0x1e00
	v_mfma_f32_32x32x16_bf16 v[32:47], v[114:117], v[122:125], v[32:47]
	ds_read_b64_tr_b16 v[122:123], v161 offset:0x2600
	ds_read_b64_tr_b16 v[124:125], v161 offset:0x2e00
	ds_read_b64_tr_b16 v[136:137], v161 offset:0x3600
	ds_read_b64_tr_b16 v[138:139], v161 offset:0x3e00
	s_waitcnt lgkmcnt(0)
	v_mfma_f32_32x32x16_bf16 v[32:47], v[100:103], v[132:135], v[32:47]
	v_mfma_f32_32x32x16_bf16 v[16:31], v[110:113], v[96:99], v[16:31]
	v_max_f32_e32 v126, v81, v81
	v_max_f32_e32 v127, v80, v80
	v_max_f32_e32 v126, v127, v126
	v_max3_f32 v126, v126, v82, v83
	v_max3_f32 v126, v126, v84, v85
	v_max3_f32 v96, v126, v86, v87
	v_max3_f32 v96, v96, v88, v89
	v_max3_f32 v96, v96, v90, v91
	v_mfma_f32_32x32x16_bf16 v[16:31], v[104:107], v[118:121], v[16:31]
	v_max3_f32 v96, v96, v92, v93
	v_max3_f32 v96, v96, v94, v95
	v_max3_f32 v96, v96, v64, v65
	v_max3_f32 v96, v96, v66, v67
	v_max3_f32 v96, v96, v68, v69
	v_max3_f32 v96, v96, v70, v71
	v_max3_f32 v96, v96, v72, v73
	v_max3_f32 v96, v96, v74, v75
	v_mfma_f32_32x32x16_bf16 v[16:31], v[114:117], v[122:125], v[16:31]
	v_max3_f32 v96, v96, v76, v77
	v_max3_f32 v96, v96, v78, v79
	v_mov_b32_e32 v97, v96
	s_nop 1
	v_permlane32_swap_b32_e32 v96, v97
	v_max_f32_e32 v97, v97, v97
	v_max_f32_e32 v96, v96, v96
	v_max_f32_e32 v96, v96, v97
	v_max_f32_e32 v97, v175, v175
	v_max_f32_e32 v97, v97, v96
	v_sub_f32_e32 v98, v96, v175
	v_mfma_f32_32x32x16_bf16 v[16:31], v[100:103], v[136:139], v[16:31]
	v_sub_f32_e32 v96, v175, v97
	v_mul_f32_e32 v96, 0x3e0293ee, v96
	v_exp_f32_e32 v96, v96
	v_cmp_ge_f32_e32 vcc, s15, v98
	s_cmp_eq_u64 vcc, exec
	s_cselect_b64 s[8:9], -1, 0
	v_cndmask_b32_e64 v96, v96, 1.0, s[8:9]
	v_cmp_gt_f32_e32 vcc, 1.0, v96
	s_waitcnt vmcnt(32)
	s_barrier
	s_cbranch_vccz .LBB0_447
	s_and_saveexec_b64 s[2:3], s[6:7]
	ds_write_b32 v158, v96 offset:128
	s_or_b64 exec, exec, s[2:3]
	s_waitcnt lgkmcnt(0)
	v_add_u32_e32 v106, v131, v128
	ds_read_b128 v[98:101], v106 offset:224
	ds_read_b128 v[102:105], v106 offset:192
	ds_read_b128 v[110:113], v106 offset:160
	ds_read_b128 v[114:117], v106 offset:128
	s_waitcnt lgkmcnt(3)
	v_pk_mul_f32 v[12:13], v[12:13], v[98:99]
	s_waitcnt lgkmcnt(2)
	v_pk_mul_f32 v[8:9], v[8:9], v[102:103]
	s_waitcnt lgkmcnt(1)
	v_pk_mul_f32 v[4:5], v[4:5], v[110:111]
	v_pk_mul_f32 v[14:15], v[14:15], v[100:101]
	v_pk_mul_f32 v[10:11], v[10:11], v[104:105]
	v_pk_mul_f32 v[6:7], v[6:7], v[112:113]
	s_waitcnt lgkmcnt(0)
	v_pk_mul_f32 v[2:3], v[2:3], v[116:117]
	v_pk_mul_f32 v[0:1], v[0:1], v[114:115]
	v_pk_mul_f32 v[60:61], v[60:61], v[98:99]
	v_pk_mul_f32 v[56:57], v[56:57], v[102:103]
	v_pk_mul_f32 v[52:53], v[52:53], v[110:111]
	v_pk_mul_f32 v[62:63], v[62:63], v[100:101]
	v_pk_mul_f32 v[58:59], v[58:59], v[104:105]
	v_pk_mul_f32 v[54:55], v[54:55], v[112:113]
	v_pk_mul_f32 v[50:51], v[50:51], v[116:117]
	v_pk_mul_f32 v[48:49], v[48:49], v[114:115]
	v_pk_mul_f32 v[44:45], v[44:45], v[98:99]
	v_pk_mul_f32 v[40:41], v[40:41], v[102:103]
	v_pk_mul_f32 v[36:37], v[36:37], v[110:111]
	v_pk_mul_f32 v[46:47], v[46:47], v[100:101]
	v_pk_mul_f32 v[42:43], v[42:43], v[104:105]
	v_pk_mul_f32 v[38:39], v[38:39], v[112:113]
	v_pk_mul_f32 v[34:35], v[34:35], v[116:117]
	v_pk_mul_f32 v[32:33], v[32:33], v[114:115]
	v_pk_mul_f32 v[28:29], v[28:29], v[98:99]
	v_pk_mul_f32 v[24:25], v[24:25], v[102:103]
	v_pk_mul_f32 v[20:21], v[20:21], v[110:111]
	v_pk_mul_f32 v[30:31], v[30:31], v[100:101]
	v_pk_mul_f32 v[26:27], v[26:27], v[104:105]
	v_pk_mul_f32 v[22:23], v[22:23], v[112:113]
	v_pk_mul_f32 v[18:19], v[18:19], v[116:117]
	v_pk_mul_f32 v[16:17], v[16:17], v[114:115]
